# SwiGLU epilogue: r^2 folded into the sigmoid denominator with one fma (one VALU op less per output); first peeled K step of a non-first tile no longer waits for the previous epilogue stores
# baseline (speedup 1.0000x reference)
.Ltb_g3_skip:
	s_mov_b64 s[2:3], 0
	s_lshl_b32 s16, s34, 7
	s_add_u32 s73, s8, s16
	s_addc_u32 s75, s9, 0
	s_add_u32 vcc_lo, s73, 0x100
	s_addc_u32 vcc_hi, s75, 0
	s_and_b64 s[86:87], s[2:3], exec
	s_cselect_b32 s87, s5, vcc_hi
	s_cselect_b32 s86, s29, vcc_lo
	v_lshl_add_u64 v[136:137], v[130:131], 0, s[16:17]
	s_mov_b64 vcc, 0x100
	s_add_i32 s16, 0, 0x10000
	v_lshl_add_u64 v[136:137], v[136:137], 0, vcc
	v_add_u32_e32 v139, s16, v188
	s_add_i32 vcc_lo, 0, 0x14000
	ds_read_b128 v[140:143], v139
	ds_read_b128 v[150:153], v139 offset:1024
	ds_read_b128 v[154:157], v139 offset:2048
	ds_read_b128 v[158:161], v139 offset:3072
	v_add_u32_e32 v139, vcc_lo, v188
	ds_read_b128 v[176:179], v139
	ds_read_b128 v[180:183], v139 offset:1024
	ds_read_b128 v[184:187], v139 offset:2048
	ds_read_b128 v[194:197], v139 offset:3072
	v_cndmask_b32_e64 v137, v137, v133, s[2:3]
	v_cndmask_b32_e64 v136, v136, v138, s[2:3]
	s_add_u32 s2, s73, 0x40080
	s_addc_u32 s3, s75, 0
	v_lshl_add_u64 v[144:145], s[2:3], 0, v[162:163]
	s_add_i32 m0, s21, 0xc000
	ds_read_b128 v[198:201], v191
	ds_read_b128 v[202:205], v191 offset:1024
	ds_read_b128 v[214:217], v191 offset:2048
	ds_read_b128 v[218:221], v191 offset:3072
	ds_read_b128 v[222:225], v191 offset:4096
	ds_read_b128 v[226:229], v191 offset:5120
	ds_read_b128 v[230:233], v191 offset:6144
	ds_read_b128 v[234:237], v191 offset:7168
	global_load_lds_dwordx4 v[144:145], off
	v_lshl_add_u64 v[144:145], s[2:3], 0, v[172:173]
	s_add_i32 m0, s21, 0xe000
	s_nop 0
	global_load_lds_dwordx4 v[144:145], off
	s_cmp_eq_u32 s41, 0
	s_cbranch_scc1 .Lpw0_first
	s_waitcnt vmcnt(10)
	s_branch .Lpw0_done
.Lpw0_first:
	s_waitcnt vmcnt(8)
.Lpw0_done:
	s_waitcnt lgkmcnt(0)
	s_barrier
	s_setprio 1
	s_waitcnt lgkmcnt(0)
	v_mfma_f32_16x16x32_bf16 v[126:129], v[140:143], v[198:201], 0
	v_mfma_f32_16x16x32_bf16 v[122:125], v[154:157], v[198:201], 0
	v_mfma_f32_16x16x32_bf16 v[118:121], v[140:143], v[214:217], 0
	v_mfma_f32_16x16x32_bf16 v[114:117], v[154:157], v[214:217], 0
	v_mfma_f32_16x16x32_bf16 v[110:113], v[140:143], v[222:225], 0
	v_mfma_f32_16x16x32_bf16 v[106:109], v[154:157], v[222:225], 0
	v_mfma_f32_16x16x32_bf16 v[102:105], v[140:143], v[230:233], 0
	v_mfma_f32_16x16x32_bf16 v[98:101], v[154:157], v[230:233], 0
	v_mfma_f32_16x16x32_bf16 v[126:129], v[150:153], v[202:205], v[126:129]
	v_mfma_f32_16x16x32_bf16 v[122:125], v[158:161], v[202:205], v[122:125]
	v_mfma_f32_16x16x32_bf16 v[118:121], v[150:153], v[218:221], v[118:121]
	v_mfma_f32_16x16x32_bf16 v[114:117], v[158:161], v[218:221], v[114:117]
	v_mfma_f32_16x16x32_bf16 v[110:113], v[150:153], v[226:229], v[110:113]
	v_mfma_f32_16x16x32_bf16 v[106:109], v[158:161], v[226:229], v[106:109]
	v_mfma_f32_16x16x32_bf16 v[102:105], v[150:153], v[234:237], v[102:105]
	v_mfma_f32_16x16x32_bf16 v[98:101], v[158:161], v[234:237], v[98:101]
	s_setprio 0
	s_setprio 1
	v_mfma_f32_16x16x32_bf16 v[94:97], v[176:179], v[198:201], 0
	v_mfma_f32_16x16x32_bf16 v[90:93], v[184:187], v[198:201], 0
	v_mfma_f32_16x16x32_bf16 v[86:89], v[176:179], v[214:217], 0
	v_mfma_f32_16x16x32_bf16 v[82:85], v[184:187], v[214:217], 0
	v_mfma_f32_16x16x32_bf16 v[78:81], v[176:179], v[222:225], 0
	v_mfma_f32_16x16x32_bf16 v[74:77], v[184:187], v[222:225], 0
	v_mfma_f32_16x16x32_bf16 v[70:73], v[176:179], v[230:233], 0
	v_mfma_f32_16x16x32_bf16 v[66:69], v[184:187], v[230:233], 0
	v_mfma_f32_16x16x32_bf16 v[94:97], v[180:183], v[202:205], v[94:97]
	v_mfma_f32_16x16x32_bf16 v[90:93], v[194:197], v[202:205], v[90:93]
	v_mfma_f32_16x16x32_bf16 v[86:89], v[180:183], v[218:221], v[86:89]
	v_mfma_f32_16x16x32_bf16 v[82:85], v[194:197], v[218:221], v[82:85]
	v_mfma_f32_16x16x32_bf16 v[78:81], v[180:183], v[226:229], v[78:81]
	v_mfma_f32_16x16x32_bf16 v[74:77], v[194:197], v[226:229], v[74:77]
	v_mfma_f32_16x16x32_bf16 v[70:73], v[180:183], v[234:237], v[70:73]
	v_mfma_f32_16x16x32_bf16 v[66:69], v[194:197], v[234:237], v[66:69]
	s_setprio 0
	s_barrier
	s_add_i32 s2, s16, s20
	v_lshl_add_u64 v[144:145], v[136:137], 0, v[164:165]
	s_mov_b32 m0, s2
	ds_read_b128 v[198:201], v191 offset:16384
	ds_read_b128 v[202:205], v191 offset:17408
	ds_read_b128 v[214:217], v191 offset:18432
	ds_read_b128 v[218:221], v191 offset:19456
	ds_read_b128 v[222:225], v191 offset:20480
	ds_read_b128 v[226:229], v191 offset:21504
	ds_read_b128 v[230:233], v191 offset:22528
	ds_read_b128 v[234:237], v191 offset:23552
	global_load_lds_dwordx4 v[144:145], off
	v_lshl_add_u64 v[166:167], v[136:137], 0, v[174:175]
	s_add_i32 m0, s2, 0x2000
	v_lshl_add_u64 v[238:239], v[136:137], 0, s[18:19]
	s_add_i32 s2, vcc_lo, s20
	global_load_lds_dwordx4 v[166:167], off
	v_lshl_add_u64 v[240:241], v[238:239], 0, v[164:165]
	s_mov_b32 m0, s2
	v_lshl_add_u64 v[238:239], v[238:239], 0, v[174:175]
	global_load_lds_dwordx4 v[240:241], off
	s_add_i32 m0, s2, 0x2000
	v_lshl_add_u64 v[240:241], s[86:87], 0, v[172:173]
	global_load_lds_dwordx4 v[238:239], off
	v_lshl_add_u64 v[238:239], s[86:87], 0, v[162:163]
	s_mov_b32 m0, s21
	s_nop 0
	global_load_lds_dwordx4 v[238:239], off
	s_mov_b32 m0, s23
	s_nop 0
	global_load_lds_dwordx4 v[240:241], off
	s_cmp_eq_u32 s41, 0
	s_cbranch_scc1 .Lpw1_first
	s_waitcnt vmcnt(16)
	s_branch .Lpw1_done

.Lpw1_done:
	s_waitcnt lgkmcnt(0)
	s_barrier
	s_setprio 1
	s_waitcnt lgkmcnt(0)
	v_mfma_f32_16x16x32_bf16 v[62:65], v[140:143], v[198:201], 0
	v_mfma_f32_16x16x32_bf16 v[58:61], v[154:157], v[198:201], 0
	v_mfma_f32_16x16x32_bf16 v[54:57], v[140:143], v[214:217], 0
	v_mfma_f32_16x16x32_bf16 v[50:53], v[154:157], v[214:217], 0
	v_mfma_f32_16x16x32_bf16 v[46:49], v[140:143], v[222:225], 0
	v_mfma_f32_16x16x32_bf16 v[42:45], v[154:157], v[222:225], 0
	v_mfma_f32_16x16x32_bf16 v[38:41], v[140:143], v[230:233], 0
	v_mfma_f32_16x16x32_bf16 v[34:37], v[154:157], v[230:233], 0
	v_mfma_f32_16x16x32_bf16 v[62:65], v[150:153], v[202:205], v[62:65]
	v_mfma_f32_16x16x32_bf16 v[58:61], v[158:161], v[202:205], v[58:61]
	v_mfma_f32_16x16x32_bf16 v[54:57], v[150:153], v[218:221], v[54:57]
	v_mfma_f32_16x16x32_bf16 v[50:53], v[158:161], v[218:221], v[50:53]
	v_mfma_f32_16x16x32_bf16 v[46:49], v[150:153], v[226:229], v[46:49]
	v_mfma_f32_16x16x32_bf16 v[42:45], v[158:161], v[226:229], v[42:45]
	v_mfma_f32_16x16x32_bf16 v[38:41], v[150:153], v[234:237], v[38:41]
	v_mfma_f32_16x16x32_bf16 v[34:37], v[158:161], v[234:237], v[34:37]
	s_setprio 0
	s_setprio 1
	v_mfma_f32_16x16x32_bf16 v[30:33], v[176:179], v[198:201], 0
	v_mfma_f32_16x16x32_bf16 v[26:29], v[184:187], v[198:201], 0
	v_mfma_f32_16x16x32_bf16 v[22:25], v[176:179], v[214:217], 0
	v_mfma_f32_16x16x32_bf16 v[18:21], v[184:187], v[214:217], 0
	v_mfma_f32_16x16x32_bf16 v[14:17], v[176:179], v[222:225], 0
	v_mfma_f32_16x16x32_bf16 v[10:13], v[184:187], v[222:225], 0
	v_mfma_f32_16x16x32_bf16 v[6:9], v[176:179], v[230:233], 0
	v_mfma_f32_16x16x32_bf16 v[2:5], v[184:187], v[230:233], 0
	v_mfma_f32_16x16x32_bf16 v[30:33], v[180:183], v[202:205], v[30:33]
	v_mfma_f32_16x16x32_bf16 v[26:29], v[194:197], v[202:205], v[26:29]
	v_mfma_f32_16x16x32_bf16 v[22:25], v[180:183], v[218:221], v[22:25]
	v_mfma_f32_16x16x32_bf16 v[18:21], v[194:197], v[218:221], v[18:21]
	v_mfma_f32_16x16x32_bf16 v[14:17], v[180:183], v[226:229], v[14:17]
	v_mfma_f32_16x16x32_bf16 v[10:13], v[194:197], v[226:229], v[10:13]
	v_mfma_f32_16x16x32_bf16 v[6:9], v[180:183], v[234:237], v[6:9]
	v_mfma_f32_16x16x32_bf16 v[2:5], v[194:197], v[234:237], v[2:5]
	s_setprio 0
	s_barrier
	s_add_i32 s16, 0, 0x18000
	v_add_u32_e32 v139, s16, v188
	s_add_i32 s73, 0, 0x1c000
	ds_read_b128 v[140:143], v139
	ds_read_b128 v[150:153], v139 offset:1024
	ds_read_b128 v[154:157], v139 offset:2048
	ds_read_b128 v[158:161], v139 offset:3072
	v_add_u32_e32 v139, s73, v188
	ds_read_b128 v[176:179], v139
	ds_read_b128 v[180:183], v139 offset:1024
	ds_read_b128 v[184:187], v139 offset:2048
	ds_read_b128 v[194:197], v139 offset:3072
	s_add_u32 s2, s86, 0x40000
	s_addc_u32 s3, s87, 0
	s_mov_b32 m0, s26
	v_lshl_add_u64 v[242:243], s[2:3], 0, v[162:163]
	ds_read_b128 v[198:201], v191 offset:32768
	ds_read_b128 v[202:205], v191 offset:33792
	ds_read_b128 v[214:217], v191 offset:34816
	ds_read_b128 v[218:221], v191 offset:35840
	ds_read_b128 v[222:225], v191 offset:36864
	ds_read_b128 v[226:229], v191 offset:37888
	ds_read_b128 v[230:233], v191 offset:38912
	ds_read_b128 v[234:237], v191 offset:39936
	global_load_lds_dwordx4 v[242:243], off
	v_lshl_add_u64 v[242:243], s[2:3], 0, v[172:173]
	s_mov_b32 m0, s27
	s_nop 0
	global_load_lds_dwordx4 v[242:243], off
	s_waitcnt vmcnt(8)
	s_waitcnt lgkmcnt(0)
	s_barrier
	s_setprio 1
	s_waitcnt lgkmcnt(0)
	v_mfma_f32_16x16x32_bf16 v[126:129], v[140:143], v[198:201], v[126:129]
	v_mfma_f32_16x16x32_bf16 v[122:125], v[154:157], v[198:201], v[122:125]
	v_mfma_f32_16x16x32_bf16 v[118:121], v[140:143], v[214:217], v[118:121]
	v_mfma_f32_16x16x32_bf16 v[114:117], v[154:157], v[214:217], v[114:117]
	v_mfma_f32_16x16x32_bf16 v[110:113], v[140:143], v[222:225], v[110:113]
	v_mfma_f32_16x16x32_bf16 v[106:109], v[154:157], v[222:225], v[106:109]
	v_mfma_f32_16x16x32_bf16 v[102:105], v[140:143], v[230:233], v[102:105]
	v_mfma_f32_16x16x32_bf16 v[98:101], v[154:157], v[230:233], v[98:101]
	v_mfma_f32_16x16x32_bf16 v[126:129], v[150:153], v[202:205], v[126:129]
	v_mfma_f32_16x16x32_bf16 v[122:125], v[158:161], v[202:205], v[122:125]
	v_mfma_f32_16x16x32_bf16 v[118:121], v[150:153], v[218:221], v[118:121]
	v_mfma_f32_16x16x32_bf16 v[114:117], v[158:161], v[218:221], v[114:117]
	v_mfma_f32_16x16x32_bf16 v[110:113], v[150:153], v[226:229], v[110:113]
	v_mfma_f32_16x16x32_bf16 v[106:109], v[158:161], v[226:229], v[106:109]
	v_mfma_f32_16x16x32_bf16 v[102:105], v[150:153], v[234:237], v[102:105]
	v_mfma_f32_16x16x32_bf16 v[98:101], v[158:161], v[234:237], v[98:101]
	s_setprio 0
	s_setprio 1
	v_mfma_f32_16x16x32_bf16 v[94:97], v[176:179], v[198:201], v[94:97]
	v_mfma_f32_16x16x32_bf16 v[90:93], v[184:187], v[198:201], v[90:93]
	v_mfma_f32_16x16x32_bf16 v[86:89], v[176:179], v[214:217], v[86:89]
	v_mfma_f32_16x16x32_bf16 v[82:85], v[184:187], v[214:217], v[82:85]
	v_mfma_f32_16x16x32_bf16 v[78:81], v[176:179], v[222:225], v[78:81]
	v_mfma_f32_16x16x32_bf16 v[74:77], v[184:187], v[222:225], v[74:77]
	v_mfma_f32_16x16x32_bf16 v[70:73], v[176:179], v[230:233], v[70:73]
	v_mfma_f32_16x16x32_bf16 v[66:69], v[184:187], v[230:233], v[66:69]
	v_mfma_f32_16x16x32_bf16 v[94:97], v[180:183], v[202:205], v[94:97]
	v_mfma_f32_16x16x32_bf16 v[90:93], v[194:197], v[202:205], v[90:93]
	v_mfma_f32_16x16x32_bf16 v[86:89], v[180:183], v[218:221], v[86:89]
	v_mfma_f32_16x16x32_bf16 v[82:85], v[194:197], v[218:221], v[82:85]
	v_mfma_f32_16x16x32_bf16 v[78:81], v[180:183], v[226:229], v[78:81]
	v_mfma_f32_16x16x32_bf16 v[74:77], v[194:197], v[226:229], v[74:77]
	v_mfma_f32_16x16x32_bf16 v[70:73], v[180:183], v[234:237], v[70:73]
	v_mfma_f32_16x16x32_bf16 v[66:69], v[194:197], v[234:237], v[66:69]
	s_setprio 0
	s_barrier
	s_add_i32 s2, s16, s20
	v_lshl_add_u64 v[144:145], v[144:145], 0, s[14:15]
	s_mov_b32 m0, s2
	ds_read_b128 v[198:201], v191 offset:49152
	ds_read_b128 v[202:205], v191 offset:50176
	ds_read_b128 v[214:217], v191 offset:51200
	ds_read_b128 v[218:221], v191 offset:52224
	ds_read_b128 v[222:225], v191 offset:53248
	ds_read_b128 v[226:229], v191 offset:54272
	ds_read_b128 v[230:233], v191 offset:55296
	ds_read_b128 v[234:237], v191 offset:56320
	global_load_lds_dwordx4 v[144:145], off
	s_add_i32 m0, s2, 0x2000
	s_mov_b64 s[2:3], 0x40080
	v_lshl_add_u64 v[144:145], v[166:167], 0, s[14:15]
	v_lshl_add_u64 v[136:137], v[136:137], 0, s[2:3]
	s_add_i32 s2, s73, s20
	global_load_lds_dwordx4 v[144:145], off
	v_lshl_add_u64 v[144:145], v[136:137], 0, v[164:165]
	s_mov_b32 m0, s2
	v_lshl_add_u64 v[136:137], v[136:137], 0, v[174:175]
	global_load_lds_dwordx4 v[144:145], off
	s_add_i32 m0, s2, 0x2000
	s_nop 0
	global_load_lds_dwordx4 v[136:137], off
	v_lshl_add_u64 v[136:137], v[238:239], 0, s[14:15]
	s_mov_b32 m0, s91
	s_nop 0
	global_load_lds_dwordx4 v[136:137], off
	v_lshl_add_u64 v[136:137], v[240:241], 0, s[14:15]
	s_mov_b32 m0, s92
	s_nop 0
	global_load_lds_dwordx4 v[136:137], off
	s_waitcnt vmcnt(8)
	s_waitcnt lgkmcnt(0)
	s_barrier
	s_setprio 1
	s_waitcnt lgkmcnt(0)
	v_mfma_f32_16x16x32_bf16 v[62:65], v[140:143], v[198:201], v[62:65]
	v_mfma_f32_16x16x32_bf16 v[58:61], v[154:157], v[198:201], v[58:61]
	v_mfma_f32_16x16x32_bf16 v[54:57], v[140:143], v[214:217], v[54:57]
	v_mfma_f32_16x16x32_bf16 v[50:53], v[154:157], v[214:217], v[50:53]
	v_mfma_f32_16x16x32_bf16 v[46:49], v[140:143], v[222:225], v[46:49]
	v_mfma_f32_16x16x32_bf16 v[42:45], v[154:157], v[222:225], v[42:45]
	v_mfma_f32_16x16x32_bf16 v[38:41], v[140:143], v[230:233], v[38:41]
	v_mfma_f32_16x16x32_bf16 v[34:37], v[154:157], v[230:233], v[34:37]
	v_mfma_f32_16x16x32_bf16 v[62:65], v[150:153], v[202:205], v[62:65]
	v_mfma_f32_16x16x32_bf16 v[58:61], v[158:161], v[202:205], v[58:61]
	v_mfma_f32_16x16x32_bf16 v[54:57], v[150:153], v[218:221], v[54:57]
	v_mfma_f32_16x16x32_bf16 v[50:53], v[158:161], v[218:221], v[50:53]
	v_mfma_f32_16x16x32_bf16 v[46:49], v[150:153], v[226:229], v[46:49]
	v_mfma_f32_16x16x32_bf16 v[42:45], v[158:161], v[226:229], v[42:45]
	v_mfma_f32_16x16x32_bf16 v[38:41], v[150:153], v[234:237], v[38:41]
	v_mfma_f32_16x16x32_bf16 v[34:37], v[158:161], v[234:237], v[34:37]
	s_setprio 0
	s_setprio 1
	v_mfma_f32_16x16x32_bf16 v[30:33], v[176:179], v[198:201], v[30:33]
	v_mfma_f32_16x16x32_bf16 v[26:29], v[184:187], v[198:201], v[26:29]
	v_mfma_f32_16x16x32_bf16 v[22:25], v[176:179], v[214:217], v[22:25]
	v_mfma_f32_16x16x32_bf16 v[18:21], v[184:187], v[214:217], v[18:21]
	v_mfma_f32_16x16x32_bf16 v[14:17], v[176:179], v[222:225], v[14:17]
	v_mfma_f32_16x16x32_bf16 v[10:13], v[184:187], v[222:225], v[10:13]
	v_mfma_f32_16x16x32_bf16 v[6:9], v[176:179], v[230:233], v[6:9]
	v_mfma_f32_16x16x32_bf16 v[2:5], v[184:187], v[230:233], v[2:5]
	v_mfma_f32_16x16x32_bf16 v[30:33], v[180:183], v[202:205], v[30:33]
	v_mfma_f32_16x16x32_bf16 v[26:29], v[194:197], v[202:205], v[26:29]
	v_mfma_f32_16x16x32_bf16 v[22:25], v[180:183], v[218:221], v[22:25]
	v_mfma_f32_16x16x32_bf16 v[18:21], v[194:197], v[218:221], v[18:21]
	v_mfma_f32_16x16x32_bf16 v[14:17], v[180:183], v[226:229], v[14:17]
	v_mfma_f32_16x16x32_bf16 v[10:13], v[194:197], v[226:229], v[10:13]
	v_mfma_f32_16x16x32_bf16 v[6:9], v[180:183], v[234:237], v[6:9]
	v_mfma_f32_16x16x32_bf16 v[2:5], v[194:197], v[234:237], v[2:5]
	s_setprio 0
	s_barrier
	s_mov_b32 s34, 2

.LBB0_340:
	s_movk_i32 s16, 0x1600
	s_mov_b32 s5, s17
	v_mul_u32_u24_e32 v144, 0x1600, v136
	v_lshl_add_u32 v144, v192, 8, v144
	v_add3_u32 v144, v144, s4, v0
	v_mul_f32_e32 v137, v142, v142
	v_mul_f32_e32 v133, 0xbfb8aa3b, v142
	v_rcp_f32_e32 v137, v137
	v_mul_f32_e32 v94, v126, v94
	v_mul_f32_e32 v95, v127, v95
	v_mul_f32_e32 v96, v128, v96
	v_mul_f32_e32 v97, v129, v97
	v_mul_f32_e32 v90, v122, v90
	v_mul_f32_e32 v91, v123, v91
	v_mul_f32_e32 v92, v124, v92
	v_mul_f32_e32 v93, v125, v93
	v_mul_f32_e32 v126, v133, v126
	v_mul_f32_e32 v127, v133, v127
	v_mul_f32_e32 v128, v133, v128
	v_mul_f32_e32 v129, v133, v129
	v_mul_f32_e32 v122, v133, v122
	v_mul_f32_e32 v123, v133, v123
	v_mul_f32_e32 v124, v133, v124
	v_mul_f32_e32 v125, v133, v125
	v_exp_f32_e32 v126, v126
	v_exp_f32_e32 v127, v127
	v_exp_f32_e32 v128, v128
	v_exp_f32_e32 v129, v129
	v_exp_f32_e32 v122, v122
	v_exp_f32_e32 v123, v123
	v_exp_f32_e32 v124, v124
	v_exp_f32_e32 v125, v125
	v_fma_f32 v126, v126, v137, v137
	v_fma_f32 v127, v127, v137, v137
	v_fma_f32 v128, v128, v137, v137
	v_fma_f32 v129, v129, v137, v137
	v_fma_f32 v122, v122, v137, v137
	v_fma_f32 v123, v123, v137, v137
	v_fma_f32 v124, v124, v137, v137
	v_fma_f32 v125, v125, v137, v137
	v_rcp_f32_e32 v126, v126
	v_rcp_f32_e32 v127, v127
	v_rcp_f32_e32 v128, v128
	v_rcp_f32_e32 v129, v129
	v_rcp_f32_e32 v122, v122
	v_rcp_f32_e32 v123, v123
	v_rcp_f32_e32 v124, v124
	v_rcp_f32_e32 v125, v125
	v_mul_f32_e32 v94, v126, v94
	v_mul_f32_e32 v95, v127, v95
	v_mul_f32_e32 v96, v128, v96
	v_mul_f32_e32 v97, v129, v97
	v_mul_f32_e32 v90, v122, v90
	v_mul_f32_e32 v91, v123, v91
	v_mul_f32_e32 v92, v124, v92
	v_mul_f32_e32 v93, v125, v93
	v_cvt_pk_bf16_f32 v94, v94, v95
	v_cvt_pk_bf16_f32 v95, v96, v97
	v_cvt_pk_bf16_f32 v96, v90, v91
	v_cvt_pk_bf16_f32 v97, v92, v93
	global_store_dwordx4 v144, v[94:97], s[52:53]
	v_mul_f32_e32 v161, v158, v158
	v_mul_f32_e32 v145, 0xbfb8aa3b, v158
	v_rcp_f32_e32 v161, v161
	v_mul_f32_e32 v86, v118, v86
	v_mul_f32_e32 v87, v119, v87
	v_mul_f32_e32 v88, v120, v88
	v_mul_f32_e32 v89, v121, v89
	v_mul_f32_e32 v82, v114, v82
	v_mul_f32_e32 v83, v115, v83
	v_mul_f32_e32 v84, v116, v84
	v_mul_f32_e32 v85, v117, v85
	v_mul_f32_e32 v118, v145, v118
	v_mul_f32_e32 v119, v145, v119
	v_mul_f32_e32 v120, v145, v120
	v_mul_f32_e32 v121, v145, v121
	v_mul_f32_e32 v114, v145, v114
	v_mul_f32_e32 v115, v145, v115
	v_mul_f32_e32 v116, v145, v116
	v_mul_f32_e32 v117, v145, v117
	v_exp_f32_e32 v118, v118
	v_exp_f32_e32 v119, v119
	v_exp_f32_e32 v120, v120
	v_exp_f32_e32 v121, v121
	v_exp_f32_e32 v114, v114
	v_exp_f32_e32 v115, v115
	v_exp_f32_e32 v116, v116
	v_exp_f32_e32 v117, v117
	v_fma_f32 v118, v118, v161, v161
	v_fma_f32 v119, v119, v161, v161
	v_fma_f32 v120, v120, v161, v161
	v_fma_f32 v121, v121, v161, v161
	v_fma_f32 v114, v114, v161, v161
	v_fma_f32 v115, v115, v161, v161
	v_fma_f32 v116, v116, v161, v161
	v_fma_f32 v117, v117, v161, v161
	v_rcp_f32_e32 v118, v118
	v_rcp_f32_e32 v119, v119
	v_rcp_f32_e32 v120, v120
	v_rcp_f32_e32 v121, v121
	v_rcp_f32_e32 v114, v114
	v_rcp_f32_e32 v115, v115
	v_rcp_f32_e32 v116, v116
	v_rcp_f32_e32 v117, v117
	v_mul_f32_e32 v86, v118, v86
	v_mul_f32_e32 v87, v119, v87
	v_mul_f32_e32 v88, v120, v88
	v_mul_f32_e32 v89, v121, v89
	v_mul_f32_e32 v82, v114, v82
	v_mul_f32_e32 v83, v115, v83
	v_mul_f32_e32 v84, v116, v84
	v_mul_f32_e32 v85, v117, v85
	v_cvt_pk_bf16_f32 v86, v86, v87
	v_cvt_pk_bf16_f32 v87, v88, v89
	v_cvt_pk_bf16_f32 v88, v82, v83
	v_cvt_pk_bf16_f32 v89, v84, v85
	v_add_u32_e32 v160, 0x16000, v144
	global_store_dwordx4 v160, v[86:89], s[52:53]
	v_mul_f32_e32 v137, v156, v156
	v_mul_f32_e32 v133, 0xbfb8aa3b, v156
	v_rcp_f32_e32 v137, v137
	v_mul_f32_e32 v78, v110, v78
	v_mul_f32_e32 v79, v111, v79
	v_mul_f32_e32 v80, v112, v80
	v_mul_f32_e32 v81, v113, v81
	v_mul_f32_e32 v74, v106, v74
	v_mul_f32_e32 v75, v107, v75
	v_mul_f32_e32 v76, v108, v76
	v_mul_f32_e32 v77, v109, v77
	v_mul_f32_e32 v110, v133, v110
	v_mul_f32_e32 v111, v133, v111
	v_mul_f32_e32 v112, v133, v112
	v_mul_f32_e32 v113, v133, v113
	v_mul_f32_e32 v106, v133, v106
	v_mul_f32_e32 v107, v133, v107
	v_mul_f32_e32 v108, v133, v108
	v_mul_f32_e32 v109, v133, v109
	v_exp_f32_e32 v110, v110
	v_exp_f32_e32 v111, v111
	v_exp_f32_e32 v112, v112
	v_exp_f32_e32 v113, v113
	v_exp_f32_e32 v106, v106
	v_exp_f32_e32 v107, v107
	v_exp_f32_e32 v108, v108
	v_exp_f32_e32 v109, v109
	v_fma_f32 v110, v110, v137, v137
	v_fma_f32 v111, v111, v137, v137
	v_fma_f32 v112, v112, v137, v137
	v_fma_f32 v113, v113, v137, v137
	v_fma_f32 v106, v106, v137, v137
	v_fma_f32 v107, v107, v137, v137
	v_fma_f32 v108, v108, v137, v137
	v_fma_f32 v109, v109, v137, v137
	v_rcp_f32_e32 v110, v110
	v_rcp_f32_e32 v111, v111
	v_rcp_f32_e32 v112, v112
	v_rcp_f32_e32 v113, v113
	v_rcp_f32_e32 v106, v106
	v_rcp_f32_e32 v107, v107
	v_rcp_f32_e32 v108, v108
	v_rcp_f32_e32 v109, v109
	v_mul_f32_e32 v78, v110, v78
	v_mul_f32_e32 v79, v111, v79
	v_mul_f32_e32 v80, v112, v80
	v_mul_f32_e32 v81, v113, v81
	v_mul_f32_e32 v74, v106, v74
	v_mul_f32_e32 v75, v107, v75
	v_mul_f32_e32 v76, v108, v76
	v_mul_f32_e32 v77, v109, v77
	v_cvt_pk_bf16_f32 v78, v78, v79
	v_cvt_pk_bf16_f32 v79, v80, v81
	v_cvt_pk_bf16_f32 v80, v74, v75
	v_cvt_pk_bf16_f32 v81, v76, v77
	v_add_u32_e32 v160, 0x2c000, v144
	global_store_dwordx4 v160, v[78:81], s[52:53]
	v_mul_f32_e32 v161, v154, v154
	v_mul_f32_e32 v145, 0xbfb8aa3b, v154
	v_rcp_f32_e32 v161, v161
	v_mul_f32_e32 v70, v102, v70
	v_mul_f32_e32 v71, v103, v71
	v_mul_f32_e32 v72, v104, v72
	v_mul_f32_e32 v73, v105, v73
	v_mul_f32_e32 v66, v98, v66
	v_mul_f32_e32 v67, v99, v67
	v_mul_f32_e32 v68, v100, v68
	v_mul_f32_e32 v69, v101, v69
	v_mul_f32_e32 v102, v145, v102
	v_mul_f32_e32 v103, v145, v103
	v_mul_f32_e32 v104, v145, v104
	v_mul_f32_e32 v105, v145, v105
	v_mul_f32_e32 v98, v145, v98
	v_mul_f32_e32 v99, v145, v99
	v_mul_f32_e32 v100, v145, v100
	v_mul_f32_e32 v101, v145, v101
	v_exp_f32_e32 v102, v102
	v_exp_f32_e32 v103, v103
	v_exp_f32_e32 v104, v104
	v_exp_f32_e32 v105, v105
	v_exp_f32_e32 v98, v98
	v_exp_f32_e32 v99, v99
	v_exp_f32_e32 v100, v100
	v_exp_f32_e32 v101, v101
	v_fma_f32 v102, v102, v161, v161
	v_fma_f32 v103, v103, v161, v161
	v_fma_f32 v104, v104, v161, v161
	v_fma_f32 v105, v105, v161, v161
	v_fma_f32 v98, v98, v161, v161
	v_fma_f32 v99, v99, v161, v161
	v_fma_f32 v100, v100, v161, v161
	v_fma_f32 v101, v101, v161, v161
	v_rcp_f32_e32 v102, v102
	v_rcp_f32_e32 v103, v103
	v_rcp_f32_e32 v104, v104
	v_rcp_f32_e32 v105, v105
	v_rcp_f32_e32 v98, v98
	v_rcp_f32_e32 v99, v99
	v_rcp_f32_e32 v100, v100
	v_rcp_f32_e32 v101, v101
	v_mul_f32_e32 v70, v102, v70
	v_mul_f32_e32 v71, v103, v71
	v_mul_f32_e32 v72, v104, v72
	v_mul_f32_e32 v73, v105, v73
	v_mul_f32_e32 v66, v98, v66
	v_mul_f32_e32 v67, v99, v67
	v_mul_f32_e32 v68, v100, v68
	v_mul_f32_e32 v69, v101, v69
	v_cvt_pk_bf16_f32 v70, v70, v71
	v_cvt_pk_bf16_f32 v71, v72, v73
	v_cvt_pk_bf16_f32 v72, v66, v67
	v_cvt_pk_bf16_f32 v73, v68, v69
	v_add_u32_e32 v160, 0x42000, v144
	global_store_dwordx4 v160, v[70:73], s[52:53]
	v_mul_f32_e32 v137, v152, v152
	v_mul_f32_e32 v133, 0xbfb8aa3b, v152
	v_rcp_f32_e32 v137, v137
	v_mul_f32_e32 v30, v62, v30
	v_mul_f32_e32 v31, v63, v31
	v_mul_f32_e32 v32, v64, v32
	v_mul_f32_e32 v33, v65, v33
	v_mul_f32_e32 v26, v58, v26
	v_mul_f32_e32 v27, v59, v27
	v_mul_f32_e32 v28, v60, v28
	v_mul_f32_e32 v29, v61, v29
	v_mul_f32_e32 v62, v133, v62
	v_mul_f32_e32 v63, v133, v63
	v_mul_f32_e32 v64, v133, v64
	v_mul_f32_e32 v65, v133, v65
	v_mul_f32_e32 v58, v133, v58
	v_mul_f32_e32 v59, v133, v59
	v_mul_f32_e32 v60, v133, v60
	v_mul_f32_e32 v61, v133, v61
	v_exp_f32_e32 v62, v62
	v_exp_f32_e32 v63, v63
	v_exp_f32_e32 v64, v64
	v_exp_f32_e32 v65, v65
	v_exp_f32_e32 v58, v58
	v_exp_f32_e32 v59, v59
	v_exp_f32_e32 v60, v60
	v_exp_f32_e32 v61, v61
	v_fma_f32 v62, v62, v137, v137
	v_fma_f32 v63, v63, v137, v137
	v_fma_f32 v64, v64, v137, v137
	v_fma_f32 v65, v65, v137, v137
	v_fma_f32 v58, v58, v137, v137
	v_fma_f32 v59, v59, v137, v137
	v_fma_f32 v60, v60, v137, v137
	v_fma_f32 v61, v61, v137, v137
	v_rcp_f32_e32 v62, v62
	v_rcp_f32_e32 v63, v63
	v_rcp_f32_e32 v64, v64
	v_rcp_f32_e32 v65, v65
	v_rcp_f32_e32 v58, v58
	v_rcp_f32_e32 v59, v59
	v_rcp_f32_e32 v60, v60
	v_rcp_f32_e32 v61, v61
	v_mul_f32_e32 v30, v62, v30
	v_mul_f32_e32 v31, v63, v31
	v_mul_f32_e32 v32, v64, v32
	v_mul_f32_e32 v33, v65, v33
	v_mul_f32_e32 v26, v58, v26
	v_mul_f32_e32 v27, v59, v27
	v_mul_f32_e32 v28, v60, v28
	v_mul_f32_e32 v29, v61, v29
	v_cvt_pk_bf16_f32 v30, v30, v31
	v_cvt_pk_bf16_f32 v31, v32, v33
	v_cvt_pk_bf16_f32 v32, v26, v27
	v_cvt_pk_bf16_f32 v33, v28, v29
	v_add_u32_e32 v160, 0xb0000, v144
	global_store_dwordx4 v160, v[30:33], s[52:53]
	v_mul_f32_e32 v161, v150, v150
	v_mul_f32_e32 v145, 0xbfb8aa3b, v150
	v_rcp_f32_e32 v161, v161
	v_mul_f32_e32 v22, v54, v22
	v_mul_f32_e32 v23, v55, v23
	v_mul_f32_e32 v24, v56, v24
	v_mul_f32_e32 v25, v57, v25
	v_mul_f32_e32 v18, v50, v18
	v_mul_f32_e32 v19, v51, v19
	v_mul_f32_e32 v20, v52, v20
	v_mul_f32_e32 v21, v53, v21
	v_mul_f32_e32 v54, v145, v54
	v_mul_f32_e32 v55, v145, v55
	v_mul_f32_e32 v56, v145, v56
	v_mul_f32_e32 v57, v145, v57
	v_mul_f32_e32 v50, v145, v50
	v_mul_f32_e32 v51, v145, v51
	v_mul_f32_e32 v52, v145, v52
	v_mul_f32_e32 v53, v145, v53
	v_exp_f32_e32 v54, v54
	v_exp_f32_e32 v55, v55
	v_exp_f32_e32 v56, v56
	v_exp_f32_e32 v57, v57
	v_exp_f32_e32 v50, v50
	v_exp_f32_e32 v51, v51
	v_exp_f32_e32 v52, v52
	v_exp_f32_e32 v53, v53
	v_fma_f32 v54, v54, v161, v161
	v_fma_f32 v55, v55, v161, v161
	v_fma_f32 v56, v56, v161, v161
	v_fma_f32 v57, v57, v161, v161
	v_fma_f32 v50, v50, v161, v161
	v_fma_f32 v51, v51, v161, v161
	v_fma_f32 v52, v52, v161, v161
	v_fma_f32 v53, v53, v161, v161
	v_rcp_f32_e32 v54, v54
	v_rcp_f32_e32 v55, v55
	v_rcp_f32_e32 v56, v56
	v_rcp_f32_e32 v57, v57
	v_rcp_f32_e32 v50, v50
	v_rcp_f32_e32 v51, v51
	v_rcp_f32_e32 v52, v52
	v_rcp_f32_e32 v53, v53
	v_mul_f32_e32 v22, v54, v22
	v_mul_f32_e32 v23, v55, v23
	v_mul_f32_e32 v24, v56, v24
	v_mul_f32_e32 v25, v57, v25
	v_mul_f32_e32 v18, v50, v18
	v_mul_f32_e32 v19, v51, v19
	v_mul_f32_e32 v20, v52, v20
	v_mul_f32_e32 v21, v53, v21
	v_cvt_pk_bf16_f32 v22, v22, v23
	v_cvt_pk_bf16_f32 v23, v24, v25
	v_cvt_pk_bf16_f32 v24, v18, v19
	v_cvt_pk_bf16_f32 v25, v20, v21
	v_add_u32_e32 v160, 0xc6000, v144
	global_store_dwordx4 v160, v[22:25], s[52:53]
	v_mul_f32_e32 v137, v140, v140
	v_mul_f32_e32 v133, 0xbfb8aa3b, v140
	v_rcp_f32_e32 v137, v137
	v_mul_f32_e32 v14, v46, v14
	v_mul_f32_e32 v15, v47, v15
	v_mul_f32_e32 v16, v48, v16
	v_mul_f32_e32 v17, v49, v17
	v_mul_f32_e32 v10, v42, v10
	v_mul_f32_e32 v11, v43, v11
	v_mul_f32_e32 v12, v44, v12
	v_mul_f32_e32 v13, v45, v13
	v_mul_f32_e32 v46, v133, v46
	v_mul_f32_e32 v47, v133, v47
	v_mul_f32_e32 v48, v133, v48
	v_mul_f32_e32 v49, v133, v49
	v_mul_f32_e32 v42, v133, v42
	v_mul_f32_e32 v43, v133, v43
	v_mul_f32_e32 v44, v133, v44
	v_mul_f32_e32 v45, v133, v45
	v_exp_f32_e32 v46, v46
	v_exp_f32_e32 v47, v47
	v_exp_f32_e32 v48, v48
	v_exp_f32_e32 v49, v49
	v_exp_f32_e32 v42, v42
	v_exp_f32_e32 v43, v43
	v_exp_f32_e32 v44, v44
	v_exp_f32_e32 v45, v45
	v_fma_f32 v46, v46, v137, v137
	v_fma_f32 v47, v47, v137, v137
	v_fma_f32 v48, v48, v137, v137
	v_fma_f32 v49, v49, v137, v137
	v_fma_f32 v42, v42, v137, v137
	v_fma_f32 v43, v43, v137, v137
	v_fma_f32 v44, v44, v137, v137
	v_fma_f32 v45, v45, v137, v137
	v_rcp_f32_e32 v46, v46
	v_rcp_f32_e32 v47, v47
	v_rcp_f32_e32 v48, v48
	v_rcp_f32_e32 v49, v49
	v_rcp_f32_e32 v42, v42
	v_rcp_f32_e32 v43, v43
	v_rcp_f32_e32 v44, v44
	v_rcp_f32_e32 v45, v45
	v_mul_f32_e32 v14, v46, v14
	v_mul_f32_e32 v15, v47, v15
	v_mul_f32_e32 v16, v48, v16
	v_mul_f32_e32 v17, v49, v17
	v_mul_f32_e32 v10, v42, v10
	v_mul_f32_e32 v11, v43, v11
	v_mul_f32_e32 v12, v44, v12
	v_mul_f32_e32 v13, v45, v13
	v_cvt_pk_bf16_f32 v14, v14, v15
	v_cvt_pk_bf16_f32 v15, v16, v17
	v_cvt_pk_bf16_f32 v16, v10, v11
	v_cvt_pk_bf16_f32 v17, v12, v13
	v_add_u32_e32 v160, 0xdc000, v144
	global_store_dwordx4 v160, v[14:17], s[52:53]
	v_mul_f32_e32 v161, v138, v138
	v_mul_f32_e32 v145, 0xbfb8aa3b, v138
	v_rcp_f32_e32 v161, v161
	v_mul_f32_e32 v6, v38, v6
	v_mul_f32_e32 v7, v39, v7
	v_mul_f32_e32 v8, v40, v8
	v_mul_f32_e32 v9, v41, v9
	v_mul_f32_e32 v2, v34, v2
	v_mul_f32_e32 v3, v35, v3
	v_mul_f32_e32 v4, v36, v4
	v_mul_f32_e32 v5, v37, v5
	v_mul_f32_e32 v38, v145, v38
	v_mul_f32_e32 v39, v145, v39
	v_mul_f32_e32 v40, v145, v40
	v_mul_f32_e32 v41, v145, v41
	v_mul_f32_e32 v34, v145, v34
	v_mul_f32_e32 v35, v145, v35
	v_mul_f32_e32 v36, v145, v36
	v_mul_f32_e32 v37, v145, v37
	v_exp_f32_e32 v38, v38
	v_exp_f32_e32 v39, v39
	v_exp_f32_e32 v40, v40
	v_exp_f32_e32 v41, v41
	v_exp_f32_e32 v34, v34
	v_exp_f32_e32 v35, v35
	v_exp_f32_e32 v36, v36
	v_exp_f32_e32 v37, v37
	v_fma_f32 v38, v38, v161, v161
	v_fma_f32 v39, v39, v161, v161
	v_fma_f32 v40, v40, v161, v161
	v_fma_f32 v41, v41, v161, v161
	v_fma_f32 v34, v34, v161, v161
	v_fma_f32 v35, v35, v161, v161
	v_fma_f32 v36, v36, v161, v161
	v_fma_f32 v37, v37, v161, v161
	v_rcp_f32_e32 v38, v38
	v_rcp_f32_e32 v39, v39
	v_rcp_f32_e32 v40, v40
	v_rcp_f32_e32 v41, v41
	v_rcp_f32_e32 v34, v34
	v_rcp_f32_e32 v35, v35
	v_rcp_f32_e32 v36, v36
	v_rcp_f32_e32 v37, v37
	v_mul_f32_e32 v6, v38, v6
	v_mul_f32_e32 v7, v39, v7
	v_mul_f32_e32 v8, v40, v8
	v_mul_f32_e32 v9, v41, v9
	v_mul_f32_e32 v2, v34, v2
	v_mul_f32_e32 v3, v35, v3
	v_mul_f32_e32 v4, v36, v4
	v_mul_f32_e32 v5, v37, v5
	v_cvt_pk_bf16_f32 v6, v6, v7
	v_cvt_pk_bf16_f32 v7, v8, v9
	v_cvt_pk_bf16_f32 v8, v2, v3
	v_cvt_pk_bf16_f32 v9, v4, v5
	v_add_u32_e32 v160, 0xf2000, v144
	global_store_dwordx4 v160, v[6:9], s[52:53]
	s_and_b64 s[2:3], s[0:1], s[2:3]
	s_andn2_b64 vcc, exec, s[2:3]
	s_cbranch_vccnz .LBB0_348
	s_waitcnt vmcnt(0)
	s_and_saveexec_b64 s[2:3], s[44:45]
	s_cbranch_execz .LBB0_347
	s_mov_b64 s[84:85], exec
	v_mbcnt_lo_u32_b32 v133, s84, 0
	v_mbcnt_hi_u32_b32 v133, s85, v133
	v_cmp_eq_u32_e32 vcc, 0, v133
	s_and_saveexec_b64 s[82:83], vcc
	s_cbranch_execz .LBB0_344
	s_bcnt1_i32_b64 s5, s[84:85]
	v_mov_b32_e32 v136, s5
	s_waitcnt vmcnt(0)
	ds_add_rtn_u32 v136, v207, v136
